# barrier invalidate issued after the leader decision: leader's write-back and release adds go in front of its invalidate; others invalidate right before their first poll
# baseline (speedup 1.0000x reference)
; __device__ __forceinline__ unsigned xb_ld(unsigned* p)              { return __hip_atomic_load(p, __ATOMIC_RELAXED, __HIP_MEMORY_SCOPE_AGENT); }
; __device__ __forceinline__ unsigned xb_add(unsigned* p, unsigned v) { return __hip_atomic_fetch_add(p, v, __ATOMIC_RELAXED, __HIP_MEMORY_SCOPE_AGENT); }
; #define XB_SPIN(cond, bar) do { unsigned _sp = 0; while (cond) { __builtin_amdgcn_s_sleep(1); \
;     if ((++_sp & 255u) == 0u) { if (xb_ld(&(bar)[XB_TMO])) break; if (_sp > XB_SPIN_CAP) { atomicAdd(&(bar)[XB_TMO], 1u); break; } } } } while (0)
; __device__ __forceinline__ void xcd_barrier(const XcdBarrier& b) {
;     asm volatile("s_waitcnt vmcnt(0)" ::: "memory");
;     __syncthreads();
;     if (threadIdx.x == 0) {
;         unsigned* bar = b.bar;
;         __builtin_amdgcn_s_waitcnt(0);
;         unsigned nloc = b.st[0], nx = b.st[1];
;         if (nloc == 0u) { xcd_barrier_complete(bar, b.x, nloc, nx); b.st[0] = nloc; b.st[1] = nx; }
;         const unsigned old = xb_add(&bar[XB_XSUB(b.x)], 1u);
;         const unsigned gen = old / nloc;
;         if (old + 1u == (gen + 1u) * nloc) {
;             __builtin_amdgcn_fence(__ATOMIC_RELEASE, "agent");
;             asm volatile("s_waitcnt vmcnt(0)" ::: "memory");
;             const unsigned og = xb_add(&bar[XB_TOP], 1u);
;             const unsigned tg = og / nx;
;             if (og + 1u == (tg + 1u) * nx) xb_add(&bar[XB_TOPGEN], 1u);
;             else XB_SPIN(xb_ld(&bar[XB_TOPGEN]) == tg, bar);
;             __builtin_amdgcn_fence(__ATOMIC_ACQUIRE, "agent");
;             xb_add(&bar[XB_XGEN(b.x)], 1u);
;             asm volatile("s_waitcnt vmcnt(0)" ::: "memory");
;         } else {
;             XB_SPIN(xb_ld(&bar[XB_XGEN(b.x)]) == gen, bar);
;             __builtin_amdgcn_fence(__ATOMIC_ACQUIRE, "agent");
;             asm volatile("s_waitcnt vmcnt(0)" ::: "memory");
;         }
.LBB0_151:
	s_waitcnt lgkmcnt(0)
	v_readfirstlane_b32 s14, v2
	v_readfirstlane_b32 s15, v0
	s_lshl_b32 s4, s3, 8
	s_add_u32 s6, s78, 0x1701400
	s_addc_u32 s7, s79, 0
	s_add_u32 s6, s6, s4
	s_addc_u32 s7, s7, 0
	s_add_u32 s10, s78, 0x1703c00
	s_addc_u32 s11, s79, 0
	s_lshr_b32 s4, s4, 1
	s_add_u32 s8, s10, s4
	s_addc_u32 s9, s11, 0
	v_mov_b32_e32 v0, 0
	v_mov_b32_e32 v1, 1
	global_atomic_add v2, v0, v1, s[6:7] sc0
	s_waitcnt vmcnt(0)
	v_readfirstlane_b32 s4, v2
	s_nop 3
	s_add_i32 s4, s4, 1
	s_cmp_lg_u32 s4, s14
	s_cbranch_scc1 .Lxb_local_p
	global_atomic_add v0, v1, s[10:11] offset:0
	global_atomic_add v0, v1, s[10:11] offset:128
	global_atomic_add v0, v1, s[10:11] offset:256
	global_atomic_add v0, v1, s[10:11] offset:384
	global_atomic_add v0, v1, s[10:11] offset:512
	global_atomic_add v0, v1, s[10:11] offset:640
	global_atomic_add v0, v1, s[10:11] offset:768
	global_atomic_add v0, v1, s[10:11] offset:896
.Lxb_local_p:
	buffer_inv sc1
	s_mov_b32 s4, 0

; __device__ __forceinline__ unsigned xb_ld(unsigned* p)              { return __hip_atomic_load(p, __ATOMIC_RELAXED, __HIP_MEMORY_SCOPE_AGENT); }
; __device__ __forceinline__ unsigned xb_add(unsigned* p, unsigned v) { return __hip_atomic_fetch_add(p, v, __ATOMIC_RELAXED, __HIP_MEMORY_SCOPE_AGENT); }
; #define XB_SPIN(cond, bar) do { unsigned _sp = 0; while (cond) { __builtin_amdgcn_s_sleep(1); \
;     if ((++_sp & 255u) == 0u) { if (xb_ld(&(bar)[XB_TMO])) break; if (_sp > XB_SPIN_CAP) { atomicAdd(&(bar)[XB_TMO], 1u); break; } } } } while (0)
; __device__ __forceinline__ void xcd_barrier(const XcdBarrier& b) {
;     asm volatile("s_waitcnt vmcnt(0)" ::: "memory");
;     __syncthreads();
;     if (threadIdx.x == 0) {
;         unsigned* bar = b.bar;
;         __builtin_amdgcn_s_waitcnt(0);
;         unsigned nloc = b.st[0], nx = b.st[1];
;         if (nloc == 0u) { xcd_barrier_complete(bar, b.x, nloc, nx); b.st[0] = nloc; b.st[1] = nx; }
;         const unsigned old = xb_add(&bar[XB_XSUB(b.x)], 1u);
;         const unsigned gen = old / nloc;
;         if (old + 1u == (gen + 1u) * nloc) {
;             __builtin_amdgcn_fence(__ATOMIC_RELEASE, "agent");
;             asm volatile("s_waitcnt vmcnt(0)" ::: "memory");
;             const unsigned og = xb_add(&bar[XB_TOP], 1u);
;             const unsigned tg = og / nx;
;             if (og + 1u == (tg + 1u) * nx) xb_add(&bar[XB_TOPGEN], 1u);
;             else XB_SPIN(xb_ld(&bar[XB_TOPGEN]) == tg, bar);
;             __builtin_amdgcn_fence(__ATOMIC_ACQUIRE, "agent");
;             xb_add(&bar[XB_XGEN(b.x)], 1u);
;             asm volatile("s_waitcnt vmcnt(0)" ::: "memory");
.LBB0_207:
	s_getreg_b32 s2, hwreg(HW_REG_XCC_ID, 0, 4)
	s_waitcnt vmcnt(0)
	s_barrier
	s_mov_b64 s[0:1], exec
	v_readlane_b32 s4, v253, 2
	v_readlane_b32 s5, v253, 3
	s_and_b64 s[4:5], s[0:1], s[4:5]
	s_mov_b64 exec, s[4:5]
	s_cbranch_execz .LBB0_259
	v_mov_b32_e32 v0, 0x20020
	s_waitcnt vmcnt(0) lgkmcnt(0)
	ds_read2_b32 v[2:3], v0 offset1:1
	s_and_b32 s3, s2, 15
	s_lshl_b32 s3, s3, 8
	s_add_u32 s6, s78, 0x1701400
	s_addc_u32 s7, s79, 0
	s_add_u32 s6, s6, s3
	s_addc_u32 s7, s7, 0
	s_add_u32 s10, s78, 0x1703c00
	s_addc_u32 s11, s79, 0
	s_lshr_b32 s3, s3, 1
	s_add_u32 s8, s10, s3
	s_addc_u32 s9, s11, 0
	s_waitcnt lgkmcnt(0)
	v_readfirstlane_b32 s30, v2
	v_readfirstlane_b32 s31, v3
	s_nop 3
	s_cmp_eq_u32 s30, 0
	s_cbranch_scc1 .Lxb_slow_n
	s_lshl_b32 s29, s66, 2
	s_add_i32 s29, s29, 1
	global_atomic_add v2, v173, v212, s[6:7] sc0
	s_add_i32 s32, s29, 1
	s_mul_i32 s5, s32, s30
	s_mul_i32 s32, s32, s31
	s_waitcnt vmcnt(0)
	v_readfirstlane_b32 s3, v2
	s_nop 3
	s_add_i32 s3, s3, 1
	s_cmp_lg_u32 s3, s5
	s_cbranch_scc1 .Lxb_local_n
	global_atomic_add v173, v212, s[10:11] offset:0
	global_atomic_add v173, v212, s[10:11] offset:128
	global_atomic_add v173, v212, s[10:11] offset:256
	global_atomic_add v173, v212, s[10:11] offset:384
	global_atomic_add v173, v212, s[10:11] offset:512
	global_atomic_add v173, v212, s[10:11] offset:640
	global_atomic_add v173, v212, s[10:11] offset:768
	global_atomic_add v173, v212, s[10:11] offset:896
.Lxb_local_n:
	buffer_inv sc1
	s_mov_b32 s3, 0

; __device__ __forceinline__ unsigned xb_ld(unsigned* p)              { return __hip_atomic_load(p, __ATOMIC_RELAXED, __HIP_MEMORY_SCOPE_AGENT); }
; __device__ __forceinline__ unsigned xb_add(unsigned* p, unsigned v) { return __hip_atomic_fetch_add(p, v, __ATOMIC_RELAXED, __HIP_MEMORY_SCOPE_AGENT); }
; #define XB_SPIN(cond, bar) do { unsigned _sp = 0; while (cond) { __builtin_amdgcn_s_sleep(1); \
;     if ((++_sp & 255u) == 0u) { if (xb_ld(&(bar)[XB_TMO])) break; if (_sp > XB_SPIN_CAP) { atomicAdd(&(bar)[XB_TMO], 1u); break; } } } } while (0)
; __device__ __forceinline__ void xcd_barrier(const XcdBarrier& b) {
;     asm volatile("s_waitcnt vmcnt(0)" ::: "memory");
;     __syncthreads();
;     if (threadIdx.x == 0) {
;         unsigned* bar = b.bar;
;         __builtin_amdgcn_s_waitcnt(0);
;         unsigned nloc = b.st[0], nx = b.st[1];
;         if (nloc == 0u) { xcd_barrier_complete(bar, b.x, nloc, nx); b.st[0] = nloc; b.st[1] = nx; }
;         const unsigned old = xb_add(&bar[XB_XSUB(b.x)], 1u);
;         const unsigned gen = old / nloc;
;         if (old + 1u == (gen + 1u) * nloc) {
;             __builtin_amdgcn_fence(__ATOMIC_RELEASE, "agent");
;             asm volatile("s_waitcnt vmcnt(0)" ::: "memory");
;             const unsigned og = xb_add(&bar[XB_TOP], 1u);
;             const unsigned tg = og / nx;
;             if (og + 1u == (tg + 1u) * nx) xb_add(&bar[XB_TOPGEN], 1u);
;             else XB_SPIN(xb_ld(&bar[XB_TOPGEN]) == tg, bar);
;             __builtin_amdgcn_fence(__ATOMIC_ACQUIRE, "agent");
;             xb_add(&bar[XB_XGEN(b.x)], 1u);
;             asm volatile("s_waitcnt vmcnt(0)" ::: "memory");
.LBB0_386:
	s_getreg_b32 s2, hwreg(HW_REG_XCC_ID, 0, 4)
	s_waitcnt vmcnt(0)
	v_writelane_b32 v255, s0, 13
	s_waitcnt vmcnt(0)
	s_barrier
	v_writelane_b32 v255, s1, 14
	s_mov_b64 s[0:1], exec
	v_readlane_b32 s4, v253, 2
	v_readlane_b32 s5, v253, 3
	s_and_b64 s[4:5], s[0:1], s[4:5]
	s_mov_b64 exec, s[4:5]
	s_cbranch_execz .LBB0_439
	v_mov_b32_e32 v0, 0x20020
	s_waitcnt vmcnt(0) lgkmcnt(0)
	ds_read2_b32 v[2:3], v0 offset1:1
	s_and_b32 s3, s2, 15
	s_lshl_b32 s3, s3, 8
	s_add_u32 s6, s78, 0x1701400
	s_addc_u32 s7, s79, 0
	s_add_u32 s6, s6, s3
	s_addc_u32 s7, s7, 0
	s_add_u32 s10, s78, 0x1703c00
	s_addc_u32 s11, s79, 0
	s_lshr_b32 s3, s3, 1
	s_add_u32 s8, s10, s3
	s_addc_u32 s9, s11, 0
	s_waitcnt lgkmcnt(0)
	v_readfirstlane_b32 s30, v2
	v_readfirstlane_b32 s31, v3
	s_nop 3
	s_cmp_eq_u32 s30, 0
	s_cbranch_scc1 .Lxb_slow_i
	s_lshl_b32 s29, s66, 2
	s_add_i32 s29, s29, 2
	global_atomic_add v2, v173, v212, s[6:7] sc0
	s_add_i32 s32, s29, 1
	s_mul_i32 s5, s32, s30
	s_mul_i32 s32, s32, s31
	s_waitcnt vmcnt(0)
	v_readfirstlane_b32 s3, v2
	s_nop 3
	s_add_i32 s3, s3, 1
	s_cmp_lg_u32 s3, s5
	s_cbranch_scc1 .Lxb_local_i
	buffer_wbl2 sc1
	s_waitcnt vmcnt(0)
	global_atomic_add v173, v212, s[10:11] offset:0
	global_atomic_add v173, v212, s[10:11] offset:128
	global_atomic_add v173, v212, s[10:11] offset:256
	global_atomic_add v173, v212, s[10:11] offset:384
	global_atomic_add v173, v212, s[10:11] offset:512
	global_atomic_add v173, v212, s[10:11] offset:640
	global_atomic_add v173, v212, s[10:11] offset:768
	global_atomic_add v173, v212, s[10:11] offset:896

; __device__ __forceinline__ unsigned xb_ld(unsigned* p)              { return __hip_atomic_load(p, __ATOMIC_RELAXED, __HIP_MEMORY_SCOPE_AGENT); }
; __device__ __forceinline__ unsigned xb_add(unsigned* p, unsigned v) { return __hip_atomic_fetch_add(p, v, __ATOMIC_RELAXED, __HIP_MEMORY_SCOPE_AGENT); }
; #define XB_SPIN(cond, bar) do { unsigned _sp = 0; while (cond) { __builtin_amdgcn_s_sleep(1); \
;     if ((++_sp & 255u) == 0u) { if (xb_ld(&(bar)[XB_TMO])) break; if (_sp > XB_SPIN_CAP) { atomicAdd(&(bar)[XB_TMO], 1u); break; } } } } while (0)
; __device__ __forceinline__ void xcd_barrier(const XcdBarrier& b) {
;     asm volatile("s_waitcnt vmcnt(0)" ::: "memory");
;     __syncthreads();
;     if (threadIdx.x == 0) {
;         unsigned* bar = b.bar;
;         __builtin_amdgcn_s_waitcnt(0);
;         unsigned nloc = b.st[0], nx = b.st[1];
;         if (nloc == 0u) { xcd_barrier_complete(bar, b.x, nloc, nx); b.st[0] = nloc; b.st[1] = nx; }
;         const unsigned old = xb_add(&bar[XB_XSUB(b.x)], 1u);
;         const unsigned gen = old / nloc;
;         if (old + 1u == (gen + 1u) * nloc) {
;             __builtin_amdgcn_fence(__ATOMIC_RELEASE, "agent");
;             asm volatile("s_waitcnt vmcnt(0)" ::: "memory");
;             const unsigned og = xb_add(&bar[XB_TOP], 1u);
;             const unsigned tg = og / nx;
;             if (og + 1u == (tg + 1u) * nx) xb_add(&bar[XB_TOPGEN], 1u);
;             else XB_SPIN(xb_ld(&bar[XB_TOPGEN]) == tg, bar);
;             __builtin_amdgcn_fence(__ATOMIC_ACQUIRE, "agent");
;             xb_add(&bar[XB_XGEN(b.x)], 1u);
;             asm volatile("s_waitcnt vmcnt(0)" ::: "memory");
.LBB0_534:
	s_and_b64 vcc, exec, s[0:1]
	s_mov_b32 s93, s4
	s_cbranch_vccz .LBB0_441
	s_getreg_b32 s2, hwreg(HW_REG_XCC_ID, 0, 4)
	s_waitcnt vmcnt(0)
	s_barrier
	s_mov_b64 s[0:1], exec
	v_readlane_b32 s4, v253, 2
	v_readlane_b32 s5, v253, 3
	v_readlane_b32 s72, v254, 48
	v_readlane_b32 s80, v254, 50
	v_readlane_b32 s82, v254, 52
	v_readlane_b32 s92, v254, 54
	v_readlane_b32 s94, v254, 56
	v_readlane_b32 s98, v254, 58
	v_readlane_b32 s54, v254, 60
	v_readlane_b32 s56, v254, 62
	v_readlane_b32 s60, v255, 0
	v_readlane_b32 s62, v255, 2
	v_readlane_b32 s22, v255, 21
	s_and_b64 s[4:5], s[0:1], s[4:5]
	v_readlane_b32 s73, v254, 49
	v_readlane_b32 s81, v254, 51
	v_readlane_b32 s83, v254, 53
	v_readlane_b32 s93, v254, 55
	v_readlane_b32 s95, v254, 57
	v_readlane_b32 s99, v254, 59
	v_readlane_b32 s55, v254, 61
	v_readlane_b32 s57, v254, 63
	v_readlane_b32 s61, v255, 1
	v_readlane_b32 s63, v255, 3
	v_readlane_b32 s33, v255, 4
	v_readlane_b32 s85, v255, 5
	v_readlane_b32 s25, v254, 41
	v_readlane_b32 s28, v254, 43
	v_readlane_b32 s23, v255, 22
	s_mov_b64 exec, s[4:5]
	s_cbranch_execz .LBB0_587
	v_mov_b32_e32 v0, 0x20020
	s_waitcnt vmcnt(0) lgkmcnt(0)
	ds_read2_b32 v[2:3], v0 offset1:1
	s_and_b32 s3, s2, 15
	s_lshl_b32 s3, s3, 8
	s_add_u32 s6, s78, 0x1701400
	s_addc_u32 s7, s79, 0
	s_add_u32 s6, s6, s3
	s_addc_u32 s7, s7, 0
	s_add_u32 s10, s78, 0x1703c00
	s_addc_u32 s11, s79, 0
	s_lshr_b32 s3, s3, 1
	s_add_u32 s8, s10, s3
	s_addc_u32 s9, s11, 0
	s_waitcnt lgkmcnt(0)
	v_readfirstlane_b32 s30, v2
	v_readfirstlane_b32 s31, v3
	s_nop 3
	s_cmp_eq_u32 s30, 0
	s_cbranch_scc1 .Lxb_slow_m
	v_readlane_b32 s29, v255, 21
	s_nop 3
	s_lshl_b32 s29, s29, 2
	s_add_i32 s29, s29, 3
	global_atomic_add v2, v173, v212, s[6:7] sc0
	s_add_i32 s32, s29, 1
	s_mul_i32 s5, s32, s30
	s_mul_i32 s32, s32, s31
	s_waitcnt vmcnt(0)
	v_readfirstlane_b32 s3, v2
	s_nop 3
	s_add_i32 s3, s3, 1
	s_cmp_lg_u32 s3, s5
	s_cbranch_scc1 .Lxb_local_m
	buffer_wbl2 sc1
	s_waitcnt vmcnt(0)
	global_atomic_add v173, v212, s[10:11] offset:0
	global_atomic_add v173, v212, s[10:11] offset:128
	global_atomic_add v173, v212, s[10:11] offset:256
	global_atomic_add v173, v212, s[10:11] offset:384
	global_atomic_add v173, v212, s[10:11] offset:512
	global_atomic_add v173, v212, s[10:11] offset:640
	global_atomic_add v173, v212, s[10:11] offset:768
	global_atomic_add v173, v212, s[10:11] offset:896

; __device__ __forceinline__ unsigned xb_ld(unsigned* p)              { return __hip_atomic_load(p, __ATOMIC_RELAXED, __HIP_MEMORY_SCOPE_AGENT); }
; __device__ __forceinline__ unsigned xb_add(unsigned* p, unsigned v) { return __hip_atomic_fetch_add(p, v, __ATOMIC_RELAXED, __HIP_MEMORY_SCOPE_AGENT); }
; #define XB_SPIN(cond, bar) do { unsigned _sp = 0; while (cond) { __builtin_amdgcn_s_sleep(1); \
;     if ((++_sp & 255u) == 0u) { if (xb_ld(&(bar)[XB_TMO])) break; if (_sp > XB_SPIN_CAP) { atomicAdd(&(bar)[XB_TMO], 1u); break; } } } } while (0)
; __device__ __forceinline__ void xcd_barrier(const XcdBarrier& b) {
;     asm volatile("s_waitcnt vmcnt(0)" ::: "memory");
;     __syncthreads();
;     if (threadIdx.x == 0) {
;         unsigned* bar = b.bar;
;         __builtin_amdgcn_s_waitcnt(0);
;         unsigned nloc = b.st[0], nx = b.st[1];
;         if (nloc == 0u) { xcd_barrier_complete(bar, b.x, nloc, nx); b.st[0] = nloc; b.st[1] = nx; }
;         const unsigned old = xb_add(&bar[XB_XSUB(b.x)], 1u);
;         const unsigned gen = old / nloc;
;         if (old + 1u == (gen + 1u) * nloc) {
;             __builtin_amdgcn_fence(__ATOMIC_RELEASE, "agent");
;             asm volatile("s_waitcnt vmcnt(0)" ::: "memory");
;             const unsigned og = xb_add(&bar[XB_TOP], 1u);
;             const unsigned tg = og / nx;
;             if (og + 1u == (tg + 1u) * nx) xb_add(&bar[XB_TOPGEN], 1u);
;             else XB_SPIN(xb_ld(&bar[XB_TOPGEN]) == tg, bar);
;             __builtin_amdgcn_fence(__ATOMIC_ACQUIRE, "agent");
;             xb_add(&bar[XB_XGEN(b.x)], 1u);
;             asm volatile("s_waitcnt vmcnt(0)" ::: "memory");
; __global__ void __launch_bounds__(512, 2) fwd_megakernel(Args a) {
;     ...
;             for (int step = 0; step < 2; ++step) {
;                 if ((step == 0) == small_first) { FRESH_TID();
;                     for (int t = bid; t < 256; t += G) g2_sample_tile((const bf16_t*)(a.ws + WS_H), (const bf16_t*)(a.ws + WS_WOUT) + (size_t)l * D * D, nullptr, XBase + (size_t)MP * D, a.out + (size_t)MP * D, l == 0 ? XB + (size_t)MP * D : nullptr, gate, lds, t, tid, lane, wave);
;                 } else {
;                     pg8::gemm_phase<pg8::EpiGate, pg8::StaticOrder, true, true>(lds, g, S, E);
;                 }
;             }
;         }
;         if (l == 0) GRID_BARRIER();
.LBB0_683:
	v_readlane_b32 s2, v255, 11
	v_readlane_b32 s3, v255, 12
	s_mov_b64 s[0:1], -1
	s_and_b64 vcc, exec, s[2:3]
	v_readlane_b32 s12, v255, 6
	s_mov_b64 s[26:27], 0x1000
	v_readlane_b32 s13, v255, 7
	s_cbranch_vccz .LBB0_190
	s_getreg_b32 s2, hwreg(HW_REG_XCC_ID, 0, 4)
	s_waitcnt vmcnt(0)
	s_barrier
	s_mov_b64 s[0:1], exec
	v_readlane_b32 s4, v253, 2
	v_readlane_b32 s5, v253, 3
	s_and_b64 s[4:5], s[0:1], s[4:5]
	s_mov_b64 exec, s[4:5]
	s_cbranch_execz .LBB0_189
	v_mov_b32_e32 v0, 0x20020
	s_waitcnt vmcnt(0) lgkmcnt(0)
	ds_read2_b32 v[2:3], v0 offset1:1
	s_and_b32 s3, s2, 15
	s_lshl_b32 s3, s3, 8
	s_add_u32 s6, s78, 0x1701400
	s_addc_u32 s7, s79, 0
	s_add_u32 s6, s6, s3
	s_addc_u32 s7, s7, 0
	s_add_u32 s10, s78, 0x1703c00
	s_addc_u32 s11, s79, 0
	s_lshr_b32 s3, s3, 1
	s_add_u32 s8, s10, s3
	s_addc_u32 s9, s11, 0
	s_waitcnt lgkmcnt(0)
	v_readfirstlane_b32 s30, v2
	v_readfirstlane_b32 s31, v3
	s_nop 3
	s_cmp_eq_u32 s30, 0
	s_cbranch_scc1 .Lxb_slow_o
	s_mov_b32 s29, 4
	global_atomic_add v2, v173, v212, s[6:7] sc0
	s_add_i32 s32, s29, 1
	s_mul_i32 s5, s32, s30
	s_mul_i32 s32, s32, s31
	s_waitcnt vmcnt(0)
	v_readfirstlane_b32 s3, v2
	s_nop 3
	s_add_i32 s3, s3, 1
	s_cmp_lg_u32 s3, s5
	s_cbranch_scc1 .Lxb_local_o
	global_atomic_add v173, v212, s[10:11] offset:0
	global_atomic_add v173, v212, s[10:11] offset:128
	global_atomic_add v173, v212, s[10:11] offset:256
	global_atomic_add v173, v212, s[10:11] offset:384
	global_atomic_add v173, v212, s[10:11] offset:512
	global_atomic_add v173, v212, s[10:11] offset:640
	global_atomic_add v173, v212, s[10:11] offset:768
	global_atomic_add v173, v212, s[10:11] offset:896
